# XCD-local seams v4: seam after ph5 also XCD-local (leaders post+check a split event for the Y/HN alias), decision cached at ph3 entry by wave 7
# baseline (speedup 1.0000x reference)
; __device__ __forceinline__ void s5_scan_phase(const Frame& F, const S5P& P, const float* __restrict__ SLOC, bf16* __restrict__ UX) {
;     for (int it = F.gw; it < 256; it += F.NGW) { const int g = it & 31, b = it >> 5, p = F.lane; const float delta = expf(P.lstep[g]); float ar, ai_; cpow(P.lre[g * 64 + p], P.lim[g * 64 + p], delta, 32.f, ar, ai_);
;         float xr = 0.f, xi = 0.f; const float* s = SLOC + ((size_t)g * 1024 + b * 128) * 128 + p; bf16* o = UX + ((size_t)g * 1024 + b * 128) * 640 + 512 + p;
.LBB0_346:
	s_cmp_lt_i32 s80, 4
	s_cselect_b64 s[0:1], -1, 0
	s_cmp_gt_i32 s81, 3
	s_cselect_b64 s[2:3], -1, 0
	s_and_b64 s[0:1], s[0:1], s[2:3]
	s_andn2_b64 vcc, exec, s[0:1]
	s_cbranch_vccnz .LBB0_414
	v_readfirstlane_b32 s98, v0
	s_cmp_ge_u32 s98, 0x1c0
	s_cbranch_scc0 .Lxl_set
	s_add_u32 s100, s78, 0x4120
	s_addc_u32 s101, s79, 0
	s_mov_b64 exec, 1
	v_mov_b32_e32 v1, 0
	global_load_dword v2, v1, s[100:101] sc1
	s_waitcnt vmcnt(0)
	v_cmp_eq_u32_e32 vcc, 0, v2
	v_cndmask_b32_e64 v2, 2, 1, vcc
	v_mov_b32_e32 v1, 0x20008
	ds_write_b32 v1, v2
	s_waitcnt lgkmcnt(0)
	s_mov_b64 exec, -1
.Lxl_set:
	v_mov_b32_e32 v56, v0
	s_mov_b32 s6, 7
	s_mov_b32 s4, 8
	s_mov_b32 s1, 9
	s_mov_b32 s1, 10
	v_readfirstlane_b32 s0, v56
	s_mov_b32 s1, 11
	s_ashr_i32 s0, s0, 6
	s_mul_i32 s0, s0, s82
	s_mov_b32 s1, 12
	s_add_i32 s0, s0, s96
	s_mov_b32 s1, 13
	s_mov_b32 s8, 14
	s_cmpk_gt_i32 s0, 0xff
	s_cbranch_scc1 .LBB0_352
	s_ashr_i32 s7, s6, 31
	s_lshl_b32 s1, s82, 3
	s_lshl_b64 s[2:3], s[6:7], 3
	s_add_u32 s2, s74, s2
	s_addc_u32 s3, s75, s3
	s_ashr_i32 s5, s4, 31
	s_lshl_b64 s[4:5], s[4:5], 3
	s_add_u32 s6, s74, s4
	s_addc_u32 s7, s75, s5
	s_ashr_i32 s9, s8, 31
	s_lshl_b64 s[4:5], s[8:9], 3
	s_add_u32 s12, s74, s4
	s_addc_u32 s13, s75, s5
	s_load_dwordx2 s[4:5], s[2:3], 0x0
	s_load_dwordx2 s[8:9], s[6:7], 0x0
	s_load_dwordx2 s[10:11], s[12:13], 0x0
	v_and_b32_e32 v3, 63, v56
	s_mov_b32 s12, 0x6dc9c883
	v_lshlrev_b32_e32 v2, 1, v3
	v_mov_b32_e32 v1, 0
	s_lshl_b32 s2, s0, 2
	s_lshl_b32 s3, s82, 5
	v_lshlrev_b32_e32 v4, 2, v3
	v_mov_b32_e32 v3, 0x500
	s_mov_b32 s18, 0x3fb8aa3b
	s_mov_b32 s19, 0xc2ce8ed0
	s_mov_b32 s20, 0x42b17218
	v_mov_b32_e32 v5, 0x7f800000
	s_mov_b32 s13, 0x3fc45f30
	s_mov_b32 s21, 0xec01000
	s_mov_b32 s22, 0xec02000
	s_mov_b32 s23, 0xec03000
	s_movk_i32 s24, 0x7fff
	s_mov_b32 s25, 0x1bc00000
	s_mov_b32 s26, 0x1bc01000
	s_mov_b32 s27, 0x1bc02000
	s_mov_b32 s28, 0x1bc03000
	s_mov_b32 s29, 0x1bc04000
	s_mov_b32 s30, 0x1bc05000
	s_mov_b32 s31, 0x1bc06000
	s_mov_b32 s33, 0x1bc07000
	s_mov_b32 s34, 0x1bc08000
	s_mov_b32 s35, 0x1bc09000
	s_mov_b64 s[14:15], 0xa000
	s_mov_b64 s[16:17], 0x4000
	s_mov_b32 s36, s0

; __device__ __forceinline__ unsigned xb_add(unsigned* p, unsigned v) { return __hip_atomic_fetch_add(p, v, __ATOMIC_RELAXED, __HIP_MEMORY_SCOPE_AGENT); }
; __device__ __forceinline__ void xcd_barrier(const XcdBarrier& b) {
;     asm volatile("s_waitcnt vmcnt(0)" ::: "memory");
;     __syncthreads();
;     if (threadIdx.x == 0) {
;         unsigned* bar = b.bar;
;         __builtin_amdgcn_s_waitcnt(0);
;         unsigned nloc = b.st[0], nx = b.st[1];
;         if (nloc == 0u) { xcd_barrier_complete(bar, b.x, nloc, nx); b.st[0] = nloc; b.st[1] = nx; }
;         const unsigned old = xb_add(&bar[XB_XSUB(b.x)], 1u);
.LBB0_530:
	s_cmp_lt_i32 s81, 7
	s_cbranch_scc1 .LBB0_584
	s_waitcnt vmcnt(0)
	s_waitcnt lgkmcnt(0)
	s_barrier
	s_mov_b64 s[4:5], exec
	v_readlane_b32 s0, v254, 1
	v_readlane_b32 s1, v254, 2
	s_and_b64 s[0:1], s[4:5], s[0:1]
	s_mov_b64 exec, s[0:1]
	s_cbranch_execz .LBB0_583
	s_add_i32 s0, 0, 0x20000
	v_mov_b32_e32 v1, s0
	s_waitcnt vmcnt(0) expcnt(0) lgkmcnt(0)
	ds_read_b32 v3, v1
	s_add_i32 s0, 0, 0x20004
	v_mov_b32_e32 v1, s0
	ds_read_b32 v1, v1
	v_mov_b32_e32 v2, 0x20008
	ds_read_b32 v2, v2
	s_waitcnt lgkmcnt(0)
	v_readfirstlane_b32 s101, v2
	s_cmp_eq_u32 s101, 1
	s_cbranch_scc0 .Lxm_0
	buffer_inv sc1

; __device__ __forceinline__ unsigned xb_ld(unsigned* p)              { return __hip_atomic_load(p, __ATOMIC_RELAXED, __HIP_MEMORY_SCOPE_AGENT); }
; __device__ __forceinline__ unsigned xb_add(unsigned* p, unsigned v) { return __hip_atomic_fetch_add(p, v, __ATOMIC_RELAXED, __HIP_MEMORY_SCOPE_AGENT); }
; #define XB_SPIN(cond, bar) do { unsigned _sp = 0; while (cond) { __builtin_amdgcn_s_sleep(1); \
;     if ((++_sp & 255u) == 0u) { if (xb_ld(&(bar)[XB_TMO])) break; if (_sp > XB_SPIN_CAP) { atomicAdd(&(bar)[XB_TMO], 1u); break; } } } } while (0)
; __device__ __forceinline__ void xcd_barrier(const XcdBarrier& b) {
;     ...
;         if (old + 1u == (gen + 1u) * nloc) {
;             __builtin_amdgcn_fence(__ATOMIC_RELEASE, "agent");
;             asm volatile("s_waitcnt vmcnt(0)" ::: "memory");
;             const unsigned og = xb_add(&bar[XB_TOP], 1u);
;             const unsigned tg = og / nx;
;             if (og + 1u == (tg + 1u) * nx) xb_add(&bar[XB_TOPGEN], 1u);
;             else XB_SPIN(xb_ld(&bar[XB_TOPGEN]) == tg, bar);
.LBB0_563:
	s_andn2_saveexec_b64 s[0:1], s[8:9]
	s_cbranch_execz .LBB0_583
	s_mov_b64 s[8:9], exec
	s_cmp_eq_u32 s101, 1
	s_cbranch_scc0 .Lxf_0
	s_add_u32 s98, s78, 0x41c0
	s_addc_u32 s99, s79, 0
	v_mov_b32_e32 v2, 0
	v_mov_b32_e32 v3, 1
	global_atomic_add v2, v3, s[98:99]
	s_add_u32 s98, s78, 0x41c0
	s_addc_u32 s99, s79, 0
	v_mov_b32_e32 v2, 0
	s_mov_b32 s100, 0
